# phase 9 AMODE GEMM: all 8 A-row loads + mix issued at loop top, lerp moved after first MFMA groups (was 4 serialized load-wait-lerp round trips); attention 3-stage pipeline
# speedup vs baseline: 1.0795x; 1.0235x over previous
.LBB0_217:
	s_add_u32 s4, s76, s0
	s_addc_u32 s5, s77, s1
	global_load_dwordx4 v[6:9], v4, s[4:5] offset:16
	global_load_dwordx4 v[10:13], v4, s[4:5]
	s_add_u32 s4, s78, s0
	s_addc_u32 s5, s79, s1
	global_load_dwordx4 v[14:17], v4, s[4:5]
	global_load_dwordx4 v[18:21], v4, s[4:5] offset:16
	s_add_u32 s0, s0, 32
	s_addc_u32 s1, s1, 0
	s_cmpk_eq_i32 s0, 0x100
	s_waitcnt vmcnt(2)
	v_max3_f32 v2, v2, |v10|, |v11|
	v_max3_f32 v2, v2, |v12|, |v13|
	s_waitcnt vmcnt(1)
	v_max3_f32 v3, v3, |v14|, |v15|
	v_max3_f32 v3, v3, |v16|, |v17|
	v_max3_f32 v2, v2, |v6|, |v7|
	s_waitcnt vmcnt(0)
	v_max3_f32 v3, v3, |v18|, |v19|
	v_max3_f32 v2, v2, |v8|, |v9|
	v_max3_f32 v3, v3, |v20|, |v21|
	s_cbranch_scc0 .LBB0_217
	s_cmpk_gt_u32 s2, 0x107f
	s_cbranch_scc1 .LBB0_227
	v_bfe_u32 v4, v1, 4, 2
	v_mul_f32_e32 v2, 0x41000000, v2
	v_mov_b32_e32 v65, 0
	v_lshlrev_b32_e32 v5, 4, v1
	v_mul_f32_e32 v2, v3, v2
	s_waitcnt lgkmcnt(0)
	s_and_b32 s28, s2, 3
	v_lshlrev_b32_e32 v8, 4, v4
	v_mov_b32_e32 v9, v65
	s_and_b32 s3, s2, 4
	s_lshr_b32 s16, s33, 3
	s_lshr_b32 s17, s2, 3
	v_and_b32_e32 v6, 0x70, v5
	v_mul_f32_e32 v5, 0x3fb8aa3b, v2
	v_lshl_add_u64 v[2:3], s[86:87], 0, v[8:9]
	s_mov_b64 s[4:5], 0xc850000
	s_lshl_b32 s0, s28, 7
	v_lshl_add_u64 v[66:67], v[2:3], 0, s[4:5]
	s_add_u32 s4, s86, s0
	v_mov_b32_e32 v7, v65
	s_addc_u32 s5, s87, 0
	v_lshl_add_u64 v[10:11], s[4:5], 0, v[6:7]
	s_mov_b64 s[4:5], 0x14c50000
	v_lshlrev_b32_e32 v64, 3, v4
	v_lshl_add_u64 v[68:69], v[10:11], 0, s[4:5]
	v_lshl_add_u64 v[2:3], s[86:87], 0, v[6:7]
	s_mov_b64 s[4:5], 0x16d50000
	v_and_b32_e32 v14, 15, v1
	v_lshl_add_u64 v[70:71], v[2:3], 0, s[4:5]
	v_lshl_add_u64 v[12:13], s[86:87], 0, v[64:65]
	s_mov_b64 s[4:5], 0x18e50000
	v_lshrrev_b32_e32 v62, 3, v1
	v_lshl_add_u64 v[72:73], v[12:13], 0, s[4:5]
	v_mul_u32_u24_e32 v7, 0x90, v14
	s_mov_b64 s[4:5], 0x14c58000
	s_movk_i32 s38, 0x4200
	v_lshrrev_b32_e32 v15, 1, v1
	v_mul_u32_u24_e32 v1, 0x48, v62
	v_add3_u32 v87, 0, v7, v8
	v_lshl_add_u64 v[74:75], v[10:11], 0, s[4:5]
	v_mad_u64_u32 v[8:9], s[4:5], v62, s38, 0
	v_lshlrev_b32_e32 v1, 1, v1
	v_or_b32_e32 v8, v8, v6
	v_add3_u32 v1, 0, v6, v1
	v_lshl_add_u64 v[6:7], s[86:87], 0, v[8:9]
	s_mov_b64 s[4:5], 0x16d50080
	v_mul_f32_e32 v2, 0xbf800347, v5
	s_movk_i32 s0, 0x1e0
	v_lshl_add_u64 v[76:77], v[6:7], 0, s[4:5]
	s_mov_b32 s4, 0x3f803f80
	s_mov_b32 s1, 0
	v_mov_b32_e32 v63, v65
	v_mov_b32_e32 v3, v2
	v_mov_b32_e32 v4, v2
	v_mov_b32_e32 v5, v2
	s_lshl_b32 s29, s28, 8
	v_and_or_b32 v86, v15, s0, v14
	v_sub_u32_e32 v88, 0, v64
	v_mov_b32_e32 v89, 0x108000
	s_mov_b32 s5, s4
	s_mov_b32 s6, s4
	s_mov_b32 s7, s4
	s_mov_b64 s[8:9], 0x8000
	s_mov_b64 s[12:13], 0x80
	v_and_b32_e32 v220, 0x3ff, v0
	v_lshrrev_b32_e32 v221, 3, v220
	v_lshrrev_b32_e32 v139, 1, v221
	v_and_b32_e32 v139, 7, v139
	v_and_b32_e32 v138, 7, v220
	v_xor_b32_e32 v139, v139, v138
	v_lshlrev_b32_e32 v139, 4, v139
	v_lshl_add_u32 v216, v221, 7, v139
	v_and_b32_e32 v221, 15, v220
	v_lshrrev_b32_e32 v139, 1, v221
	v_bfe_u32 v138, v220, 4, 2
	v_xor_b32_e32 v139, v139, v138
	v_lshlrev_b32_e32 v139, 4, v139
	v_lshl_add_u32 v217, v221, 7, v139
	v_mul_u32_u24_e32 v139, 0x90, v221
	v_lshl_add_u32 v139, v138, 3, v139
	v_add_u32_e32 v219, 0x6000, v139

.LBB0_224:
	s_lshl_b32 s0, s0, 3
	s_or_b32 s0, s0, s3
	s_lshr_b32 s42, s0, 2
	s_mul_i32 s46, s42, 0x2100
	s_lshl_b32 s42, s15, 8
	s_add_i32 s43, s46, s42
	s_lshl_b32 s14, s14, 6
	s_and_b32 s14, s14, 0xc0
	v_add_u32_e32 v64, s43, v86
	s_or_b32 s14, s14, s29
	s_or_b32 s0, s0, s28
	v_lshlrev_b64 v[80:81], 11, v[64:65]
	v_or_b32_e32 v64, 16, v64
	s_lshl_b32 s42, s14, 1
	s_lshl_b64 s[44:45], s[0:1], 6
	s_mov_b32 s43, s1
	v_lshlrev_b64 v[78:79], 11, v[64:65]
	v_or_b32_e32 v64, s46, v62
	v_lshl_add_u64 v[6:7], v[66:67], 0, s[42:43]
	v_lshlrev_b64 v[84:85], 9, v[64:65]
	v_lshl_add_u64 v[10:11], s[44:45], 0, v[62:63]
	v_lshl_add_u64 v[8:9], v[6:7], 0, v[80:81]
	v_lshl_add_u64 v[12:13], v[68:69], 0, v[84:85]
	v_mad_u64_u32 v[14:15], s[42:43], v10, s38, v[70:71]
	v_lshl_add_u64 v[6:7], v[6:7], 0, v[78:79]
	v_mad_u32_u24 v15, v11, s38, v15
	global_load_dwordx4 v[90:93], v[12:13], off
	global_load_dwordx4 v[94:97], v[14:15], off
	global_load_dwordx4 v[46:49], v[8:9], off
	global_load_dwordx4 v[42:45], v[8:9], off offset:64
	global_load_dwordx4 v[34:37], v[6:7], off
	global_load_dwordx4 v[30:33], v[6:7], off offset:64
	v_mov_b32_e32 v10, 0
	s_cmp_eq_u32 s15, 0
	v_mov_b32_e32 v11, v10
	v_mov_b32_e32 v12, v10
	v_mov_b32_e32 v13, v10
	v_mov_b32_e32 v14, v10
	v_mov_b32_e32 v15, v10
	v_mov_b32_e32 v16, v10
	v_mov_b32_e32 v17, v10
	v_mov_b32_e32 v26, v10
	v_mov_b32_e32 v27, v10
	v_mov_b32_e32 v28, v10
	v_mov_b32_e32 v29, v10
	v_mov_b32_e32 v6, v10
	v_mov_b32_e32 v7, v10
	v_mov_b32_e32 v8, v10
	v_mov_b32_e32 v9, v10
	v_mov_b32_e32 v18, v10
	v_mov_b32_e32 v19, v10
	v_mov_b32_e32 v20, v10
	v_mov_b32_e32 v21, v10
	v_mov_b32_e32 v22, v10
	v_mov_b32_e32 v23, v10
	v_mov_b32_e32 v24, v10
	v_mov_b32_e32 v25, v10
	v_mov_b32_e32 v38, v10
	v_mov_b32_e32 v39, v10
	v_mov_b32_e32 v40, v10
	v_mov_b32_e32 v41, v10
	v_mov_b32_e32 v50, v10
	v_mov_b32_e32 v51, v10
	v_mov_b32_e32 v52, v10
	v_mov_b32_e32 v53, v10
	v_mov_b32_e32 v54, v10
	v_mov_b32_e32 v55, v10
	v_mov_b32_e32 v56, v10
	v_mov_b32_e32 v57, v10
	v_mov_b32_e32 v58, v10
	v_mov_b32_e32 v59, v10
	v_mov_b32_e32 v60, v10
	v_mad_u64_u32 v[82:83], s[42:43], s0, v89, v[76:77]
	s_cselect_b32 s0, 3, 0x83
	v_lshl_add_u64 v[84:85], v[74:75], 0, v[84:85]
	v_mov_b32_e32 v61, v10
	s_barrier
	s_waitcnt vmcnt(5)
	ds_write_b128 v216, v[90:93]
	s_waitcnt vmcnt(4)
	ds_write_b128 v1, v[94:97] offset:24576
	s_waitcnt lgkmcnt(0)
	s_barrier
	global_load_dwordx4 v[204:207], v[84:85], off
	global_load_dwordx4 v[208:211], v[82:83], off
	v_lshl_add_u64 v[84:85], v[84:85], 0, s[8:9]
	v_lshl_add_u64 v[82:83], v[82:83], 0, s[12:13]
	v_mov_b64_e32 v[212:213], s[4:5]
	v_mov_b64_e32 v[214:215], s[6:7]
	s_mov_b32 s98, 0
	s_mov_b32 s39, 0
	s_add_i32 s43, s0, -1
	v_mov_b32_e32 v220, v217
	v_xor_b32_e32 v221, 64, v217
	ds_read_b128 v[140:143], v220
	ds_read_b128 v[144:147], v221
	ds_read_b128 v[148:151], v220 offset:2048
	ds_read_b128 v[152:155], v221 offset:2048
	ds_read_b128 v[156:159], v220 offset:4096
	ds_read_b128 v[160:163], v221 offset:4096
	ds_read_b128 v[164:167], v220 offset:6144
	ds_read_b128 v[168:171], v221 offset:6144
	v_mov_b32_e32 v232, 0
	v_mov_b32_e32 v233, 0
	v_mov_b32_e32 v234, 0
	v_mov_b32_e32 v235, 0
	v_mov_b32_e32 v248, 0
	v_mov_b32_e32 v249, 0
	v_mov_b32_e32 v250, 0
	v_mov_b32_e32 v251, 0
	v_mov_b32_e32 v188, 0
	v_mov_b32_e32 v189, 0
	v_mov_b32_e32 v190, 0
	v_mov_b32_e32 v191, 0
	v_mov_b32_e32 v192, 0
	v_mov_b32_e32 v193, 0
	v_mov_b32_e32 v194, 0
	v_mov_b32_e32 v195, 0
	v_mov_b32_e32 v196, 0
	v_mov_b32_e32 v197, 0
	v_mov_b32_e32 v198, 0
	v_mov_b32_e32 v199, 0
	v_mov_b32_e32 v200, 0
	v_mov_b32_e32 v201, 0
	v_mov_b32_e32 v202, 0
	v_mov_b32_e32 v203, 0
	v_add_u32_e32 v139, 0x2000, v216
	v_add_u32_e32 v64, 0x2400, v1
	s_waitcnt vmcnt(1)
	ds_write_b128 v139, v[204:207]
	s_waitcnt vmcnt(0)
	ds_write_b128 v64, v[208:211] offset:24576
	global_load_dwordx4 v[204:207], v[84:85], off
	global_load_dwordx4 v[208:211], v[82:83], off
	v_lshl_add_u64 v[84:85], v[84:85], 0, s[8:9]
	v_lshl_add_u64 v[82:83], v[82:83], 0, s[12:13]
	s_waitcnt lgkmcnt(2)
	v_mfma_f32_16x16x32_bf16 v[90:93], v[140:143], v[46:49], v[2:5]
	v_mfma_f32_16x16x32_bf16 v[106:109], v[140:143], v[34:37], v[2:5]
	v_mfma_f32_16x16x32_bf16 v[90:93], v[144:147], v[42:45], v[90:93]
	v_mfma_f32_16x16x32_bf16 v[106:109], v[144:147], v[30:33], v[106:109]
	v_mfma_f32_16x16x32_bf16 v[94:97], v[148:151], v[46:49], v[2:5]
	v_mfma_f32_16x16x32_bf16 v[110:113], v[148:151], v[34:37], v[2:5]
	v_mfma_f32_16x16x32_bf16 v[94:97], v[152:155], v[42:45], v[94:97]
	v_mfma_f32_16x16x32_bf16 v[110:113], v[152:155], v[30:33], v[110:113]
	v_mfma_f32_16x16x32_bf16 v[98:101], v[156:159], v[46:49], v[2:5]
	v_mfma_f32_16x16x32_bf16 v[114:117], v[156:159], v[34:37], v[2:5]
	v_mfma_f32_16x16x32_bf16 v[98:101], v[160:163], v[42:45], v[98:101]
	v_mfma_f32_16x16x32_bf16 v[114:117], v[160:163], v[30:33], v[114:117]
	v_mfma_f32_16x16x32_bf16 v[102:105], v[164:167], v[46:49], v[2:5]
	v_mfma_f32_16x16x32_bf16 v[118:121], v[164:167], v[34:37], v[2:5]
	v_mfma_f32_16x16x32_bf16 v[102:105], v[168:171], v[42:45], v[102:105]
	v_mfma_f32_16x16x32_bf16 v[118:121], v[168:171], v[30:33], v[118:121]
	s_waitcnt lgkmcnt(0)
.Lav3_loop:
	s_barrier
	s_add_i32 s99, s98, 1
	s_cmp_eq_u32 s99, 3
	s_cselect_b32 s99, 0, s99
	s_lshl_b32 s15, s99, 13
	v_add_u32_e32 v220, s15, v217
	v_xor_b32_e32 v221, 64, v220
	s_mul_i32 s42, s98, 0x2400
	v_add_u32_e32 v138, s42, v219
	s_add_i32 s100, s99, 1
	s_cmp_eq_u32 s100, 3
	s_cselect_b32 s100, 0, s100
	s_lshl_b32 s15, s100, 13
	v_add_u32_e32 v139, s15, v216
	s_mul_i32 s42, s100, 0x2400
	v_add_u32_e32 v64, s42, v1
	s_mov_b32 s98, s99
	ds_read_b128 v[140:143], v220
	ds_read_b128 v[144:147], v221
	ds_read_b128 v[148:151], v220 offset:2048
	ds_read_b128 v[152:155], v221 offset:2048
	ds_read_b128 v[156:159], v220 offset:4096
	ds_read_b128 v[160:163], v221 offset:4096
	ds_read_b128 v[164:167], v220 offset:6144
	ds_read_b128 v[168:171], v221 offset:6144
	v_mfma_f32_16x16x32_bf16 v[58:61], v[212:215], v[232:235], v[58:61]
	v_exp_f32_e32 v90, v90
	v_mfma_f32_16x16x32_bf16 v[54:57], v[212:215], v[248:251], v[54:57]
	v_exp_f32_e32 v91, v91
	v_mfma_f32_16x16x32_bf16 v[50:53], v[188:191], v[232:235], v[50:53]
	v_exp_f32_e32 v92, v92
	v_mfma_f32_16x16x32_bf16 v[38:41], v[188:191], v[248:251], v[38:41]
	v_exp_f32_e32 v93, v93
	v_mfma_f32_16x16x32_bf16 v[22:25], v[192:195], v[232:235], v[22:25]
	v_exp_f32_e32 v106, v106
	v_mfma_f32_16x16x32_bf16 v[18:21], v[192:195], v[248:251], v[18:21]
	v_exp_f32_e32 v107, v107
	v_mfma_f32_16x16x32_bf16 v[6:9], v[196:199], v[232:235], v[6:9]
	v_exp_f32_e32 v108, v108
	v_mfma_f32_16x16x32_bf16 v[26:29], v[196:199], v[248:251], v[26:29]
	v_exp_f32_e32 v109, v109
	v_mfma_f32_16x16x32_bf16 v[14:17], v[200:203], v[232:235], v[14:17]
	v_exp_f32_e32 v94, v94
	v_mfma_f32_16x16x32_bf16 v[10:13], v[200:203], v[248:251], v[10:13]
	v_exp_f32_e32 v95, v95
	s_waitcnt lgkmcnt(0)
	v_mfma_f32_16x16x32_bf16 v[224:227], v[140:143], v[46:49], v[2:5]
	ds_read_b64 v[172:173], v138
	ds_read_b64 v[174:175], v138 offset:32
	v_mfma_f32_16x16x32_bf16 v[240:243], v[140:143], v[34:37], v[2:5]
	ds_read_b64 v[176:177], v138 offset:2304
	ds_read_b64 v[178:179], v138 offset:2336
	ds_read_b64 v[180:181], v138 offset:4608
	v_mfma_f32_16x16x32_bf16 v[224:227], v[144:147], v[42:45], v[224:227]
	ds_read_b64 v[182:183], v138 offset:4640
	ds_read_b64 v[184:185], v138 offset:6912
	ds_read_b64 v[186:187], v138 offset:6944
	v_mfma_f32_16x16x32_bf16 v[240:243], v[144:147], v[30:33], v[240:243]
	v_exp_f32_e32 v96, v96
	v_exp_f32_e32 v97, v97
	v_exp_f32_e32 v110, v110
	v_mfma_f32_16x16x32_bf16 v[228:231], v[148:151], v[46:49], v[2:5]
	v_exp_f32_e32 v111, v111
	v_exp_f32_e32 v112, v112
	v_exp_f32_e32 v113, v113
	v_mfma_f32_16x16x32_bf16 v[244:247], v[148:151], v[34:37], v[2:5]
	s_nop 0
	v_cvt_pk_bf16_f32 v90, v90, v91
	v_cvt_pk_bf16_f32 v91, v92, v93
	v_mfma_f32_16x16x32_bf16 v[228:231], v[152:155], v[42:45], v[228:231]
	v_cvt_pk_bf16_f32 v92, v94, v95
	v_cvt_pk_bf16_f32 v93, v96, v97
	v_cvt_pk_bf16_f32 v106, v106, v107
	v_mfma_f32_16x16x32_bf16 v[244:247], v[152:155], v[30:33], v[244:247]
	v_cvt_pk_bf16_f32 v107, v108, v109
	v_cvt_pk_bf16_f32 v108, v110, v111
	v_cvt_pk_bf16_f32 v109, v112, v113
	s_waitcnt vmcnt(1)
	ds_write_b128 v139, v[204:207]
	s_waitcnt vmcnt(0)
	ds_write_b128 v64, v[208:211] offset:24576
	global_load_dwordx4 v[204:207], v[84:85], off
	global_load_dwordx4 v[208:211], v[82:83], off
	v_lshl_add_u64 v[84:85], v[84:85], 0, s[8:9]
	v_lshl_add_u64 v[82:83], v[82:83], 0, s[12:13]
	s_waitcnt lgkmcnt(2)
	v_mfma_f32_16x16x32_bf16 v[58:61], v[212:215], v[90:93], v[58:61]
	ds_read_b64 v[188:189], v138 offset:64
	v_mfma_f32_16x16x32_bf16 v[54:57], v[212:215], v[106:109], v[54:57]
	ds_read_b64 v[190:191], v138 offset:96
	ds_read_b64 v[192:193], v138 offset:2368
	v_mfma_f32_16x16x32_bf16 v[50:53], v[172:175], v[90:93], v[50:53]
	ds_read_b64 v[194:195], v138 offset:2400
	ds_read_b64 v[196:197], v138 offset:4672
	v_mfma_f32_16x16x32_bf16 v[38:41], v[172:175], v[106:109], v[38:41]
	ds_read_b64 v[198:199], v138 offset:4704
	ds_read_b64 v[200:201], v138 offset:6976
	v_mfma_f32_16x16x32_bf16 v[22:25], v[176:179], v[90:93], v[22:25]
	ds_read_b64 v[202:203], v138 offset:7008
	v_exp_f32_e32 v98, v98
	v_mfma_f32_16x16x32_bf16 v[18:21], v[176:179], v[106:109], v[18:21]
	v_exp_f32_e32 v99, v99
	v_mfma_f32_16x16x32_bf16 v[6:9], v[180:183], v[90:93], v[6:9]
	v_exp_f32_e32 v100, v100
	v_exp_f32_e32 v101, v101
	v_mfma_f32_16x16x32_bf16 v[26:29], v[180:183], v[106:109], v[26:29]
	v_exp_f32_e32 v114, v114
	v_exp_f32_e32 v115, v115
	v_mfma_f32_16x16x32_bf16 v[14:17], v[184:187], v[90:93], v[14:17]
	v_exp_f32_e32 v116, v116
	v_exp_f32_e32 v117, v117
	v_mfma_f32_16x16x32_bf16 v[10:13], v[184:187], v[106:109], v[10:13]
	v_exp_f32_e32 v102, v102
	v_exp_f32_e32 v103, v103
	v_mfma_f32_16x16x32_bf16 v[232:235], v[156:159], v[46:49], v[2:5]
	v_exp_f32_e32 v104, v104
	v_mfma_f32_16x16x32_bf16 v[248:251], v[156:159], v[34:37], v[2:5]
	v_exp_f32_e32 v105, v105
	v_exp_f32_e32 v118, v118
	v_mfma_f32_16x16x32_bf16 v[232:235], v[160:163], v[42:45], v[232:235]
	v_exp_f32_e32 v119, v119
	v_exp_f32_e32 v120, v120
	v_mfma_f32_16x16x32_bf16 v[248:251], v[160:163], v[30:33], v[248:251]
	v_exp_f32_e32 v121, v121
	s_nop 0
	v_mfma_f32_16x16x32_bf16 v[236:239], v[164:167], v[46:49], v[2:5]
	v_cvt_pk_bf16_f32 v98, v98, v99
	v_cvt_pk_bf16_f32 v99, v100, v101
	v_mfma_f32_16x16x32_bf16 v[252:255], v[164:167], v[34:37], v[2:5]
	v_cvt_pk_bf16_f32 v100, v102, v103
	v_cvt_pk_bf16_f32 v101, v104, v105
	v_mfma_f32_16x16x32_bf16 v[236:239], v[168:171], v[42:45], v[236:239]
	v_cvt_pk_bf16_f32 v114, v114, v115
	v_cvt_pk_bf16_f32 v115, v116, v117
	v_mfma_f32_16x16x32_bf16 v[252:255], v[168:171], v[30:33], v[252:255]
	v_cvt_pk_bf16_f32 v116, v118, v119
	v_cvt_pk_bf16_f32 v117, v120, v121
	s_waitcnt lgkmcnt(0)
	s_barrier
	s_add_i32 s99, s98, 1
	s_cmp_eq_u32 s99, 3
	s_cselect_b32 s99, 0, s99
	s_lshl_b32 s15, s99, 13
	v_add_u32_e32 v220, s15, v217
	v_xor_b32_e32 v221, 64, v220
	s_mul_i32 s42, s98, 0x2400
	v_add_u32_e32 v138, s42, v219
	s_add_i32 s100, s99, 1
	s_cmp_eq_u32 s100, 3
	s_cselect_b32 s100, 0, s100
	s_lshl_b32 s15, s100, 13
	v_add_u32_e32 v139, s15, v216
	s_mul_i32 s42, s100, 0x2400
	v_add_u32_e32 v64, s42, v1
	s_mov_b32 s98, s99
	ds_read_b128 v[140:143], v220
	ds_read_b128 v[144:147], v221
	ds_read_b128 v[148:151], v220 offset:2048
	ds_read_b128 v[152:155], v221 offset:2048
	ds_read_b128 v[156:159], v220 offset:4096
	ds_read_b128 v[160:163], v221 offset:4096
	ds_read_b128 v[164:167], v220 offset:6144
	ds_read_b128 v[168:171], v221 offset:6144
	v_mfma_f32_16x16x32_bf16 v[58:61], v[212:215], v[98:101], v[58:61]
	v_exp_f32_e32 v224, v224
	v_mfma_f32_16x16x32_bf16 v[54:57], v[212:215], v[114:117], v[54:57]
	v_exp_f32_e32 v225, v225
	v_mfma_f32_16x16x32_bf16 v[50:53], v[188:191], v[98:101], v[50:53]
	v_exp_f32_e32 v226, v226
	v_mfma_f32_16x16x32_bf16 v[38:41], v[188:191], v[114:117], v[38:41]
	v_exp_f32_e32 v227, v227
	v_mfma_f32_16x16x32_bf16 v[22:25], v[192:195], v[98:101], v[22:25]
	v_exp_f32_e32 v240, v240
	v_mfma_f32_16x16x32_bf16 v[18:21], v[192:195], v[114:117], v[18:21]
	v_exp_f32_e32 v241, v241
	v_mfma_f32_16x16x32_bf16 v[6:9], v[196:199], v[98:101], v[6:9]
	v_exp_f32_e32 v242, v242
	v_mfma_f32_16x16x32_bf16 v[26:29], v[196:199], v[114:117], v[26:29]
	v_exp_f32_e32 v243, v243
	v_mfma_f32_16x16x32_bf16 v[14:17], v[200:203], v[98:101], v[14:17]
	v_exp_f32_e32 v228, v228
	v_mfma_f32_16x16x32_bf16 v[10:13], v[200:203], v[114:117], v[10:13]
	v_exp_f32_e32 v229, v229
	s_waitcnt lgkmcnt(0)
	v_mfma_f32_16x16x32_bf16 v[90:93], v[140:143], v[46:49], v[2:5]
	ds_read_b64 v[172:173], v138
	ds_read_b64 v[174:175], v138 offset:32
	v_mfma_f32_16x16x32_bf16 v[106:109], v[140:143], v[34:37], v[2:5]
	ds_read_b64 v[176:177], v138 offset:2304
	ds_read_b64 v[178:179], v138 offset:2336
	ds_read_b64 v[180:181], v138 offset:4608
	v_mfma_f32_16x16x32_bf16 v[90:93], v[144:147], v[42:45], v[90:93]
	ds_read_b64 v[182:183], v138 offset:4640
	ds_read_b64 v[184:185], v138 offset:6912
	ds_read_b64 v[186:187], v138 offset:6944
	v_mfma_f32_16x16x32_bf16 v[106:109], v[144:147], v[30:33], v[106:109]
	v_exp_f32_e32 v230, v230
	v_exp_f32_e32 v231, v231
	v_exp_f32_e32 v244, v244
	v_mfma_f32_16x16x32_bf16 v[94:97], v[148:151], v[46:49], v[2:5]
	v_exp_f32_e32 v245, v245
	v_exp_f32_e32 v246, v246
	v_exp_f32_e32 v247, v247
	v_mfma_f32_16x16x32_bf16 v[110:113], v[148:151], v[34:37], v[2:5]
	s_nop 0
	v_cvt_pk_bf16_f32 v224, v224, v225
	v_cvt_pk_bf16_f32 v225, v226, v227
	v_mfma_f32_16x16x32_bf16 v[94:97], v[152:155], v[42:45], v[94:97]
	v_cvt_pk_bf16_f32 v226, v228, v229
	v_cvt_pk_bf16_f32 v227, v230, v231
	v_cvt_pk_bf16_f32 v240, v240, v241
	v_mfma_f32_16x16x32_bf16 v[110:113], v[152:155], v[30:33], v[110:113]
	v_cvt_pk_bf16_f32 v241, v242, v243
	v_cvt_pk_bf16_f32 v242, v244, v245
	v_cvt_pk_bf16_f32 v243, v246, v247
	s_waitcnt vmcnt(1)
	ds_write_b128 v139, v[204:207]
	s_waitcnt vmcnt(0)
	ds_write_b128 v64, v[208:211] offset:24576
	s_add_i32 s39, s39, 2
	s_cmp_eq_u32 s39, s43
	s_cbranch_scc1 .Lav3_nogl
	global_load_dwordx4 v[204:207], v[84:85], off
	global_load_dwordx4 v[208:211], v[82:83], off
	v_lshl_add_u64 v[84:85], v[84:85], 0, s[8:9]
	v_lshl_add_u64 v[82:83], v[82:83], 0, s[12:13]
.Lav3_nogl:
	s_waitcnt lgkmcnt(2)
	v_mfma_f32_16x16x32_bf16 v[58:61], v[212:215], v[224:227], v[58:61]
	ds_read_b64 v[188:189], v138 offset:64
	v_mfma_f32_16x16x32_bf16 v[54:57], v[212:215], v[240:243], v[54:57]
	ds_read_b64 v[190:191], v138 offset:96
	ds_read_b64 v[192:193], v138 offset:2368
	v_mfma_f32_16x16x32_bf16 v[50:53], v[172:175], v[224:227], v[50:53]
	ds_read_b64 v[194:195], v138 offset:2400
	ds_read_b64 v[196:197], v138 offset:4672
	v_mfma_f32_16x16x32_bf16 v[38:41], v[172:175], v[240:243], v[38:41]
	ds_read_b64 v[198:199], v138 offset:4704
	ds_read_b64 v[200:201], v138 offset:6976
	v_mfma_f32_16x16x32_bf16 v[22:25], v[176:179], v[224:227], v[22:25]
	ds_read_b64 v[202:203], v138 offset:7008
	v_exp_f32_e32 v232, v232
	v_mfma_f32_16x16x32_bf16 v[18:21], v[176:179], v[240:243], v[18:21]
	v_exp_f32_e32 v233, v233
	v_mfma_f32_16x16x32_bf16 v[6:9], v[180:183], v[224:227], v[6:9]
	v_exp_f32_e32 v234, v234
	v_exp_f32_e32 v235, v235
	v_mfma_f32_16x16x32_bf16 v[26:29], v[180:183], v[240:243], v[26:29]
	v_exp_f32_e32 v248, v248
	v_exp_f32_e32 v249, v249
	v_mfma_f32_16x16x32_bf16 v[14:17], v[184:187], v[224:227], v[14:17]
	v_exp_f32_e32 v250, v250
	v_exp_f32_e32 v251, v251
	v_mfma_f32_16x16x32_bf16 v[10:13], v[184:187], v[240:243], v[10:13]
	v_exp_f32_e32 v236, v236
	v_exp_f32_e32 v237, v237
	v_mfma_f32_16x16x32_bf16 v[98:101], v[156:159], v[46:49], v[2:5]
	v_exp_f32_e32 v238, v238
	v_mfma_f32_16x16x32_bf16 v[114:117], v[156:159], v[34:37], v[2:5]
	v_exp_f32_e32 v239, v239
	v_exp_f32_e32 v252, v252
	v_mfma_f32_16x16x32_bf16 v[98:101], v[160:163], v[42:45], v[98:101]
	v_exp_f32_e32 v253, v253
	v_exp_f32_e32 v254, v254
	v_mfma_f32_16x16x32_bf16 v[114:117], v[160:163], v[30:33], v[114:117]
	v_exp_f32_e32 v255, v255
	s_nop 0
	v_mfma_f32_16x16x32_bf16 v[102:105], v[164:167], v[46:49], v[2:5]
	v_cvt_pk_bf16_f32 v232, v232, v233
	v_cvt_pk_bf16_f32 v233, v234, v235
	v_mfma_f32_16x16x32_bf16 v[118:121], v[164:167], v[34:37], v[2:5]
	v_cvt_pk_bf16_f32 v234, v236, v237
	v_cvt_pk_bf16_f32 v235, v238, v239
	v_mfma_f32_16x16x32_bf16 v[102:105], v[168:171], v[42:45], v[102:105]
	v_cvt_pk_bf16_f32 v248, v248, v249
	v_cvt_pk_bf16_f32 v249, v250, v251
	v_mfma_f32_16x16x32_bf16 v[118:121], v[168:171], v[30:33], v[118:121]
	v_cvt_pk_bf16_f32 v250, v252, v253
	v_cvt_pk_bf16_f32 v251, v254, v255
	s_waitcnt lgkmcnt(0)
	s_cmp_lg_u32 s39, s43
	s_cbranch_scc1 .Lav3_loop
	s_barrier
	s_mul_i32 s42, s98, 0x2400
	v_add_u32_e32 v138, s42, v219
	ds_read_b64 v[172:173], v138
	ds_read_b64 v[174:175], v138 offset:32
	ds_read_b64 v[176:177], v138 offset:2304
	ds_read_b64 v[178:179], v138 offset:2336
	ds_read_b64 v[180:181], v138 offset:4608
	ds_read_b64 v[182:183], v138 offset:4640
	ds_read_b64 v[184:185], v138 offset:6912
	ds_read_b64 v[186:187], v138 offset:6944
	v_mfma_f32_16x16x32_bf16 v[58:61], v[212:215], v[232:235], v[58:61]
	v_exp_f32_e32 v90, v90
	v_mfma_f32_16x16x32_bf16 v[54:57], v[212:215], v[248:251], v[54:57]
	v_exp_f32_e32 v91, v91
	v_exp_f32_e32 v92, v92
	v_mfma_f32_16x16x32_bf16 v[50:53], v[188:191], v[232:235], v[50:53]
	v_exp_f32_e32 v93, v93
	v_mfma_f32_16x16x32_bf16 v[38:41], v[188:191], v[248:251], v[38:41]
	v_exp_f32_e32 v106, v106
	v_exp_f32_e32 v107, v107
	v_mfma_f32_16x16x32_bf16 v[22:25], v[192:195], v[232:235], v[22:25]
	v_exp_f32_e32 v108, v108
	v_exp_f32_e32 v109, v109
	v_mfma_f32_16x16x32_bf16 v[18:21], v[192:195], v[248:251], v[18:21]
	v_exp_f32_e32 v94, v94
	v_mfma_f32_16x16x32_bf16 v[6:9], v[196:199], v[232:235], v[6:9]
	v_exp_f32_e32 v95, v95
	v_exp_f32_e32 v96, v96
	v_mfma_f32_16x16x32_bf16 v[26:29], v[196:199], v[248:251], v[26:29]
	v_exp_f32_e32 v97, v97
	v_mfma_f32_16x16x32_bf16 v[14:17], v[200:203], v[232:235], v[14:17]
	v_exp_f32_e32 v110, v110
	v_exp_f32_e32 v111, v111
	v_mfma_f32_16x16x32_bf16 v[10:13], v[200:203], v[248:251], v[10:13]
	v_exp_f32_e32 v112, v112
	v_exp_f32_e32 v113, v113
	ds_read_b64 v[188:189], v138 offset:64
	ds_read_b64 v[190:191], v138 offset:96
	ds_read_b64 v[192:193], v138 offset:2368
	ds_read_b64 v[194:195], v138 offset:2400
	ds_read_b64 v[196:197], v138 offset:4672
	ds_read_b64 v[198:199], v138 offset:4704
	ds_read_b64 v[200:201], v138 offset:6976
	ds_read_b64 v[202:203], v138 offset:7008
	s_nop 0
	v_cvt_pk_bf16_f32 v90, v90, v91
	v_cvt_pk_bf16_f32 v91, v92, v93
	v_cvt_pk_bf16_f32 v92, v94, v95
	v_cvt_pk_bf16_f32 v93, v96, v97
	v_cvt_pk_bf16_f32 v106, v106, v107
	v_cvt_pk_bf16_f32 v107, v108, v109
	v_cvt_pk_bf16_f32 v108, v110, v111
	v_cvt_pk_bf16_f32 v109, v112, v113
	s_waitcnt lgkmcnt(8)
	v_mfma_f32_16x16x32_bf16 v[58:61], v[212:215], v[90:93], v[58:61]
	v_exp_f32_e32 v98, v98
	v_mfma_f32_16x16x32_bf16 v[54:57], v[212:215], v[106:109], v[54:57]
	v_exp_f32_e32 v99, v99
	v_exp_f32_e32 v100, v100
	v_mfma_f32_16x16x32_bf16 v[50:53], v[172:175], v[90:93], v[50:53]
	v_exp_f32_e32 v101, v101
	v_mfma_f32_16x16x32_bf16 v[38:41], v[172:175], v[106:109], v[38:41]
	v_exp_f32_e32 v114, v114
	v_exp_f32_e32 v115, v115
	v_mfma_f32_16x16x32_bf16 v[22:25], v[176:179], v[90:93], v[22:25]
	v_exp_f32_e32 v116, v116
	v_exp_f32_e32 v117, v117
	v_mfma_f32_16x16x32_bf16 v[18:21], v[176:179], v[106:109], v[18:21]
	v_exp_f32_e32 v102, v102
	v_mfma_f32_16x16x32_bf16 v[6:9], v[180:183], v[90:93], v[6:9]
	v_exp_f32_e32 v103, v103
	v_exp_f32_e32 v104, v104
	v_mfma_f32_16x16x32_bf16 v[26:29], v[180:183], v[106:109], v[26:29]
	v_exp_f32_e32 v105, v105
	v_mfma_f32_16x16x32_bf16 v[14:17], v[184:187], v[90:93], v[14:17]
	v_exp_f32_e32 v118, v118
	v_exp_f32_e32 v119, v119
	v_mfma_f32_16x16x32_bf16 v[10:13], v[184:187], v[106:109], v[10:13]
	v_exp_f32_e32 v120, v120
	v_exp_f32_e32 v121, v121
	s_nop 0
	v_cvt_pk_bf16_f32 v98, v98, v99
	v_cvt_pk_bf16_f32 v99, v100, v101
	v_cvt_pk_bf16_f32 v100, v102, v103
	v_cvt_pk_bf16_f32 v101, v104, v105
	v_cvt_pk_bf16_f32 v114, v114, v115
	v_cvt_pk_bf16_f32 v115, v116, v117
	v_cvt_pk_bf16_f32 v116, v118, v119
	v_cvt_pk_bf16_f32 v117, v120, v121
	s_waitcnt lgkmcnt(0)
	s_nop 0
	v_mfma_f32_16x16x32_bf16 v[58:61], v[212:215], v[98:101], v[58:61]
	v_mfma_f32_16x16x32_bf16 v[54:57], v[212:215], v[114:117], v[54:57]
	v_mfma_f32_16x16x32_bf16 v[50:53], v[188:191], v[98:101], v[50:53]
	v_mfma_f32_16x16x32_bf16 v[38:41], v[188:191], v[114:117], v[38:41]
	v_mfma_f32_16x16x32_bf16 v[22:25], v[192:195], v[98:101], v[22:25]
	v_mfma_f32_16x16x32_bf16 v[18:21], v[192:195], v[114:117], v[18:21]
	v_mfma_f32_16x16x32_bf16 v[6:9], v[196:199], v[98:101], v[6:9]
	v_mfma_f32_16x16x32_bf16 v[26:29], v[196:199], v[114:117], v[26:29]
	v_mfma_f32_16x16x32_bf16 v[14:17], v[200:203], v[98:101], v[14:17]
	v_mfma_f32_16x16x32_bf16 v[10:13], v[200:203], v[114:117], v[10:13]
	s_cmp_eq_u32 s0, 3
	s_cselect_b32 s98, 0, 0x4000
	s_cselect_b32 s0, 0, 0x4800
	s_add_i32 s0, s0, 0x1800
	v_add_u32_e32 v64, s0, v87
	v_add_u32_e32 v220, s98, v217
	v_xor_b32_e32 v221, 64, v220
	ds_read_b128 v[82:85], v220
	ds_read_b128 v[90:93], v221
	ds_read_b128 v[98:101], v220 offset:2048
	ds_read_b128 v[102:105], v221 offset:2048
	ds_read_b128 v[110:113], v220 offset:4096
	ds_read_b128 v[114:117], v221 offset:4096
	ds_read_b128 v[122:125], v220 offset:6144
	ds_read_b128 v[126:129], v221 offset:6144
	s_waitcnt lgkmcnt(7)
	v_mfma_f32_16x16x32_bf16 v[94:97], v[82:85], v[46:49], v[2:5]
	s_lshl_b32 s0, s14, 1
	s_add_i32 s17, s17, s16
	s_cmpk_gt_u32 s17, 0x20f
	s_waitcnt lgkmcnt(5)
	v_mfma_f32_16x16x32_bf16 v[106:109], v[98:101], v[46:49], v[2:5]
	s_waitcnt lgkmcnt(3)
	v_mfma_f32_16x16x32_bf16 v[118:121], v[110:113], v[46:49], v[2:5]
	v_mfma_f32_16x16x32_bf16 v[94:97], v[90:93], v[42:45], v[94:97]
	s_waitcnt lgkmcnt(1)
	v_mfma_f32_16x16x32_bf16 v[46:49], v[122:125], v[46:49], v[2:5]
	v_mfma_f32_16x16x32_bf16 v[106:109], v[102:105], v[42:45], v[106:109]
	s_nop 4
	v_exp_f32_e32 v130, v94
	v_exp_f32_e32 v131, v95
	v_exp_f32_e32 v132, v96
	v_exp_f32_e32 v133, v97
	v_mfma_f32_16x16x32_bf16 v[94:97], v[114:117], v[42:45], v[118:121]
	v_exp_f32_e32 v106, v106
	v_exp_f32_e32 v107, v107
	v_exp_f32_e32 v108, v108
	s_waitcnt lgkmcnt(0)
	v_mfma_f32_16x16x32_bf16 v[42:45], v[126:129], v[42:45], v[46:49]
	v_exp_f32_e32 v109, v109
	s_nop 1
	v_exp_f32_e32 v94, v94
	v_exp_f32_e32 v95, v95
	v_mfma_f32_16x16x32_bf16 v[46:49], v[82:85], v[34:37], v[2:5]
	v_exp_f32_e32 v96, v96
	v_exp_f32_e32 v97, v97
	v_cvt_pk_bf16_f32 v82, v94, v95
	v_mfma_f32_16x16x32_bf16 v[46:49], v[90:93], v[30:33], v[46:49]
	v_exp_f32_e32 v118, v42
	v_cvt_pk_bf16_f32 v83, v96, v97
	v_exp_f32_e32 v119, v43
	v_mfma_f32_16x16x32_bf16 v[90:93], v[98:101], v[34:37], v[2:5]
	v_exp_f32_e32 v120, v44
	s_nop 2
	v_exp_f32_e32 v98, v46
	v_exp_f32_e32 v99, v47
	v_mfma_f32_16x16x32_bf16 v[90:93], v[102:105], v[30:33], v[90:93]
	v_exp_f32_e32 v100, v48
	v_exp_f32_e32 v101, v49
	v_exp_f32_e32 v85, v45
	v_mfma_f32_16x16x32_bf16 v[94:97], v[110:113], v[34:37], v[2:5]
	v_cvt_pk_bf16_f32 v42, v130, v131
	s_nop 2
	v_exp_f32_e32 v102, v90
	v_exp_f32_e32 v103, v91
	v_mfma_f32_16x16x32_bf16 v[34:37], v[122:125], v[34:37], v[2:5]
	v_cvt_pk_bf16_f32 v43, v132, v133
	v_cvt_pk_bf16_f32 v44, v106, v107
	v_cvt_pk_bf16_f32 v45, v108, v109
	v_mfma_f32_16x16x32_bf16 v[46:49], v[114:117], v[30:33], v[94:97]
	v_cvt_pk_bf16_f32 v84, v118, v119
	v_cvt_pk_bf16_f32 v85, v120, v85
	s_nop 0
	v_exp_f32_e32 v94, v92
	v_exp_f32_e32 v95, v93
	v_mov_b64_e32 v[92:93], s[6:7]
	v_mov_b64_e32 v[90:91], s[4:5]
	v_mfma_f32_16x16x32_bf16 v[30:33], v[126:129], v[30:33], v[34:37]
	v_exp_f32_e32 v96, v46
	v_exp_f32_e32 v97, v47
	v_exp_f32_e32 v104, v48
	v_exp_f32_e32 v105, v49
	v_cvt_pk_bf16_f32 v34, v98, v99
	s_nop 2
	v_exp_f32_e32 v106, v30
	v_exp_f32_e32 v107, v31
	v_mfma_f32_16x16x32_bf16 v[46:49], v[90:93], v[42:45], v[58:61]
	v_cvt_pk_bf16_f32 v35, v100, v101
	v_cvt_pk_bf16_f32 v36, v102, v103
	v_cvt_pk_bf16_f32 v37, v94, v95
	v_exp_f32_e32 v58, v32
	v_exp_f32_e32 v33, v33
	v_mfma_f32_16x16x32_bf16 v[54:57], v[90:93], v[34:37], v[54:57]
	v_cvt_pk_bf16_f32 v30, v96, v97
	v_cvt_pk_bf16_f32 v31, v104, v105
	v_cvt_pk_bf16_f32 v32, v106, v107
	v_mfma_f32_16x16x32_bf16 v[46:49], v[90:93], v[82:85], v[46:49]
	v_cvt_pk_bf16_f32 v33, v58, v33
	s_nop 1
	v_mfma_f32_16x16x32_bf16 v[54:57], v[90:93], v[30:33], v[54:57]
	s_nop 3
	v_add_u32_e32 v47, v64, v88
	s_nop 2
	v_add_u32_e32 v55, 0x4800, v47
	ds_read2_b64 v[56:59], v55 offset1:4
	ds_read2_b64 v[90:93], v55 offset0:8 offset1:12
	s_waitcnt lgkmcnt(1)
	v_mfma_f32_16x16x32_bf16 v[48:51], v[56:59], v[42:45], v[50:53]
	s_nop 2
	v_add_u32_e32 v52, 0x5000, v47
	v_mfma_f32_16x16x32_bf16 v[38:41], v[56:59], v[34:37], v[38:41]
	ds_read2_b64 v[56:59], v52 offset0:32 offset1:36
	ds_read2_b64 v[94:97], v52 offset0:40 offset1:44
	v_add_u32_e32 v52, 0x5800, v47
	v_add_u32_e32 v47, 0x6000, v47
	s_waitcnt lgkmcnt(2)
	v_mfma_f32_16x16x32_bf16 v[48:51], v[90:93], v[82:85], v[48:51]
	ds_read2_b64 v[98:101], v52 offset0:64 offset1:68
	ds_read2_b64 v[102:105], v52 offset0:72 offset1:76
	v_lshl_add_u64 v[52:53], v[72:73], 0, s[0:1]
	v_mfma_f32_16x16x32_bf16 v[38:41], v[90:93], v[30:33], v[38:41]
	ds_read2_b64 v[90:93], v47 offset0:96 offset1:100
	ds_read2_b64 v[106:109], v47 offset0:104 offset1:108
	v_div_scale_f32 v47, s[42:43], v46, v46, 1.0
	v_rcp_f32_e32 v55, v47
	s_waitcnt lgkmcnt(5)
	v_mfma_f32_16x16x32_bf16 v[22:25], v[56:59], v[42:45], v[22:25]
	s_waitcnt lgkmcnt(0)
	s_barrier
	v_mfma_f32_16x16x32_bf16 v[18:21], v[56:59], v[34:37], v[18:21]
	v_fma_f32 v56, -v47, v55, 1.0
	v_fmac_f32_e32 v55, v56, v55
	v_div_scale_f32 v56, vcc, 1.0, v46, 1.0
	v_mfma_f32_16x16x32_bf16 v[6:9], v[98:101], v[42:45], v[6:9]
	v_mul_f32_e32 v57, v56, v55
	v_fma_f32 v58, -v47, v57, v56
	v_fmac_f32_e32 v57, v58, v55
	v_mfma_f32_16x16x32_bf16 v[14:17], v[90:93], v[42:45], v[14:17]
	v_fma_f32 v47, -v47, v57, v56
	v_div_fmas_f32 v47, v47, v55, v57
	v_div_fixup_f32 v46, v47, v46, 1.0
	v_mfma_f32_16x16x32_bf16 v[22:25], v[94:97], v[82:85], v[22:25]
	v_lshl_add_u64 v[56:57], v[52:53], 0, v[80:81]
	v_pk_mul_f32 v[50:51], v[46:47], v[50:51] op_sel_hi:[0,1]
	v_pk_mul_f32 v[48:49], v[46:47], v[48:49] op_sel_hi:[0,1]
	v_mfma_f32_16x16x32_bf16 v[6:9], v[102:105], v[82:85], v[6:9]
	v_cvt_pk_bf16_f32 v48, v48, v49
	s_nop 2
	v_pk_mul_f32 v[24:25], v[46:47], v[24:25] op_sel_hi:[0,1]
	v_pk_mul_f32 v[22:23], v[46:47], v[22:23] op_sel_hi:[0,1]
	v_mfma_f32_16x16x32_bf16 v[10:13], v[90:93], v[34:37], v[10:13]
	v_cvt_pk_bf16_f32 v22, v22, v23
	v_cvt_pk_bf16_f32 v23, v24, v25
	v_pk_mul_f32 v[8:9], v[46:47], v[8:9] op_sel_hi:[0,1]
	v_mfma_f32_16x16x32_bf16 v[14:17], v[106:109], v[82:85], v[14:17]
	v_mul_f32_e64 v6, v46, v6
	v_mul_f32_e64 v7, v46, v7
	global_store_dwordx2 v[56:57], v[22:23], off offset:32
	v_cvt_pk_bf16_f32 v22, v6, v7
	v_cvt_pk_bf16_f32 v23, v8, v9
	v_mfma_f32_16x16x32_bf16 v[6:9], v[106:109], v[30:33], v[10:13]
	v_cvt_pk_bf16_f32 v49, v50, v51
	global_store_dwordx2 v[56:57], v[48:49], off
	global_store_dwordx2 v[56:57], v[22:23], off offset:64
	v_pk_mul_f32 v[12:13], v[46:47], v[14:15] op_sel_hi:[0,1]
	v_div_scale_f32 v14, s[14:15], v54, v54, 1.0
	v_rcp_f32_e32 v15, v14
	v_pk_mul_f32 v[10:11], v[46:47], v[16:17] op_sel_hi:[0,1]
	v_cvt_pk_bf16_f32 v12, v12, v13
	v_cvt_pk_bf16_f32 v13, v10, v11
	v_fma_f32 v10, -v14, v15, 1.0
	v_fmac_f32_e32 v15, v10, v15
	v_div_scale_f32 v10, vcc, 1.0, v54, 1.0
	v_mul_f32_e32 v11, v10, v15
	global_store_dwordx2 v[56:57], v[12:13], off offset:96
	v_fma_f32 v12, -v14, v11, v10
	v_mfma_f32_16x16x32_bf16 v[26:29], v[98:101], v[34:37], v[26:29]
	v_fmac_f32_e32 v11, v12, v15
	v_fma_f32 v10, -v14, v11, v10
	v_div_fmas_f32 v10, v10, v15, v11
	v_mfma_f32_16x16x32_bf16 v[18:21], v[94:97], v[30:33], v[18:21]
	v_div_fixup_f32 v10, v10, v54, 1.0
	v_pk_mul_f32 v[14:15], v[10:11], v[40:41] op_sel_hi:[0,1]
	v_pk_mul_f32 v[16:17], v[10:11], v[38:39] op_sel_hi:[0,1]
	v_mfma_f32_16x16x32_bf16 v[26:29], v[102:105], v[30:33], v[26:29]
	v_lshl_add_u64 v[12:13], v[52:53], 0, v[78:79]
	v_cvt_pk_bf16_f32 v16, v16, v17
	v_cvt_pk_bf16_f32 v17, v14, v15
	global_store_dwordx2 v[12:13], v[16:17], off
	v_pk_mul_f32 v[14:15], v[10:11], v[20:21] op_sel_hi:[0,1]
	v_pk_mul_f32 v[16:17], v[10:11], v[18:19] op_sel_hi:[0,1]
	v_cvt_pk_bf16_f32 v16, v16, v17
	v_cvt_pk_bf16_f32 v17, v14, v15
	global_store_dwordx2 v[12:13], v[16:17], off offset:32
	v_pk_mul_f32 v[14:15], v[10:11], v[28:29] op_sel_hi:[0,1]
	v_pk_mul_f32 v[16:17], v[10:11], v[26:27] op_sel_hi:[0,1]
	v_pk_mul_f32 v[8:9], v[10:11], v[8:9] op_sel_hi:[0,1]
	v_pk_mul_f32 v[6:7], v[10:11], v[6:7] op_sel_hi:[0,1]
	v_cvt_pk_bf16_f32 v16, v16, v17
	v_cvt_pk_bf16_f32 v17, v14, v15
	v_cvt_pk_bf16_f32 v6, v6, v7
	v_cvt_pk_bf16_f32 v7, v8, v9
	global_store_dwordx2 v[12:13], v[16:17], off offset:64
	global_store_dwordx2 v[12:13], v[6:7], off offset:96
	s_cbranch_scc0 .LBB0_220

.LBB0_513:
	v_lshl_add_u64 v[142:143], v[204:205], 0, s[16:17]
	s_and_b32 s6, s65, 1
	v_add_co_u32_e32 v130, vcc, s43, v142
	s_nop 1
	v_addc_co_u32_e32 v131, vcc, 0, v143, vcc
	v_add_co_u32_e32 v224, vcc, s44, v142
	s_nop 1
	v_addc_co_u32_e32 v225, vcc, 0, v143, vcc
	v_add_co_u32_e32 v134, vcc, s45, v142
	s_nop 1
	v_addc_co_u32_e32 v135, vcc, 0, v143, vcc
	v_add_co_u32_e32 v228, vcc, s46, v142
	s_nop 1
	v_addc_co_u32_e32 v229, vcc, 0, v143, vcc
	v_add_co_u32_e32 v138, vcc, s47, v142
	s_nop 1
	v_addc_co_u32_e32 v139, vcc, 0, v143, vcc
	v_add_co_u32_e32 v232, vcc, s48, v142
	s_nop 1
	v_addc_co_u32_e32 v233, vcc, 0, v143, vcc
	v_add_co_u32_e32 v236, vcc, s52, v142
	s_nop 1
	v_addc_co_u32_e32 v237, vcc, 0, v143, vcc
	v_add_co_u32_e32 v142, vcc, s49, v142
	s_nop 1
	v_addc_co_u32_e32 v143, vcc, 0, v143, vcc
	global_load_dwordx4 v[244:247], v[206:207], off offset:16
	global_load_dwordx4 v[240:243], v[206:207], off
	global_load_dwordx4 v[130:133], v[130:131], off offset:128
	global_load_dwordx4 v[224:227], v[224:225], off offset:128
	global_load_dwordx4 v[134:137], v[134:135], off offset:128
	global_load_dwordx4 v[228:231], v[228:229], off offset:128
	global_load_dwordx4 v[138:141], v[138:139], off offset:128
	global_load_dwordx4 v[232:235], v[232:233], off offset:128
	global_load_dwordx4 v[236:239], v[236:237], off offset:128
	global_load_dwordx4 v[142:145], v[142:143], off offset:128
	s_mul_i32 s66, s6, 0x9000
	v_add_u32_e32 v203, s66, v218
	v_add_u32_e32 v190, s66, v189
	s_add_i32 s65, s65, 1
	ds_read_b128 v[146:149], v203
	ds_read_b128 v[150:153], v203 offset:2304
	ds_read_b128 v[154:157], v203 offset:4608
	ds_read_b128 v[158:161], v203 offset:6912
	ds_read_b128 v[174:177], v190
	ds_read_b128 v[170:173], v190 offset:2304
	ds_read_b128 v[166:169], v190 offset:4608
	ds_read_b128 v[162:165], v190 offset:6912
	s_setprio 1
	s_waitcnt lgkmcnt(3)
	v_mfma_f32_16x16x32_bf16 v[126:129], v[146:149], v[174:177], v[126:129]
	v_mfma_f32_16x16x32_bf16 v[122:125], v[150:153], v[174:177], v[122:125]
	v_mfma_f32_16x16x32_bf16 v[118:121], v[154:157], v[174:177], v[118:121]
	v_mfma_f32_16x16x32_bf16 v[114:117], v[158:161], v[174:177], v[114:117]
	s_waitcnt lgkmcnt(2)
	v_mfma_f32_16x16x32_bf16 v[110:113], v[146:149], v[170:173], v[110:113]
	v_mfma_f32_16x16x32_bf16 v[106:109], v[150:153], v[170:173], v[106:109]
	v_mfma_f32_16x16x32_bf16 v[102:105], v[154:157], v[170:173], v[102:105]
	v_mfma_f32_16x16x32_bf16 v[98:101], v[158:161], v[170:173], v[98:101]
	s_waitcnt lgkmcnt(1)
	v_mfma_f32_16x16x32_bf16 v[94:97], v[146:149], v[166:169], v[94:97]
	v_mfma_f32_16x16x32_bf16 v[90:93], v[150:153], v[166:169], v[90:93]
	v_mfma_f32_16x16x32_bf16 v[78:81], v[154:157], v[166:169], v[78:81]
	v_mfma_f32_16x16x32_bf16 v[66:69], v[158:161], v[166:169], v[66:69]
	s_waitcnt lgkmcnt(0)
	v_mfma_f32_16x16x32_bf16 v[70:73], v[146:149], v[162:165], v[70:73]
	v_mfma_f32_16x16x32_bf16 v[82:85], v[150:153], v[162:165], v[82:85]
	v_mfma_f32_16x16x32_bf16 v[74:77], v[154:157], v[162:165], v[74:77]
	v_mfma_f32_16x16x32_bf16 v[86:89], v[158:161], v[162:165], v[86:89]
	s_setprio 0
	ds_read_b128 v[162:165], v190 offset:9216
	ds_read_b128 v[166:169], v190 offset:11520
	ds_read_b128 v[170:173], v190 offset:13824
	ds_read_b128 v[174:177], v190 offset:16128
	s_setprio 1
	s_waitcnt lgkmcnt(3)
	v_mfma_f32_16x16x32_bf16 v[62:65], v[146:149], v[162:165], v[62:65]
	v_mfma_f32_16x16x32_bf16 v[58:61], v[150:153], v[162:165], v[58:61]
	v_mfma_f32_16x16x32_bf16 v[54:57], v[154:157], v[162:165], v[54:57]
	v_mfma_f32_16x16x32_bf16 v[50:53], v[158:161], v[162:165], v[50:53]
	s_waitcnt lgkmcnt(2)
	v_mfma_f32_16x16x32_bf16 v[46:49], v[146:149], v[166:169], v[46:49]
	v_mfma_f32_16x16x32_bf16 v[42:45], v[150:153], v[166:169], v[42:45]
	v_mfma_f32_16x16x32_bf16 v[38:41], v[154:157], v[166:169], v[38:41]
	v_mfma_f32_16x16x32_bf16 v[34:37], v[158:161], v[166:169], v[34:37]
	s_waitcnt lgkmcnt(1)
	v_mfma_f32_16x16x32_bf16 v[30:33], v[146:149], v[170:173], v[30:33]
	v_mfma_f32_16x16x32_bf16 v[26:29], v[150:153], v[170:173], v[26:29]
	v_mfma_f32_16x16x32_bf16 v[22:25], v[154:157], v[170:173], v[22:25]
	v_mfma_f32_16x16x32_bf16 v[18:21], v[158:161], v[170:173], v[18:21]
	s_waitcnt lgkmcnt(0)
	v_mfma_f32_16x16x32_bf16 v[14:17], v[146:149], v[174:177], v[14:17]
	v_mfma_f32_16x16x32_bf16 v[10:13], v[150:153], v[174:177], v[10:13]
	v_mfma_f32_16x16x32_bf16 v[6:9], v[154:157], v[174:177], v[6:9]
	v_mfma_f32_16x16x32_bf16 v[2:5], v[158:161], v[174:177], v[2:5]
	s_setprio 0
	s_waitcnt vmcnt(6)
	v_lshlrev_b32_e32 v248, 16, v130
	v_and_b32_e32 v249, 0xffff0000, v130
	v_lshlrev_b32_e32 v250, 16, v224
	v_and_b32_e32 v251, 0xffff0000, v224
	v_pk_fma_f32 v[248:249], v[240:241], v[250:251], v[248:249]
	v_lshlrev_b32_e32 v252, 16, v131
	v_and_b32_e32 v253, 0xffff0000, v131
	v_lshlrev_b32_e32 v254, 16, v225
	v_and_b32_e32 v255, 0xffff0000, v225
	v_pk_fma_f32 v[252:253], v[242:243], v[254:255], v[252:253]
	v_cvt_pk_bf16_f32 v130, v248, v249
	v_lshlrev_b32_e32 v248, 16, v132
	v_and_b32_e32 v249, 0xffff0000, v132
	v_lshlrev_b32_e32 v250, 16, v226
	v_and_b32_e32 v251, 0xffff0000, v226
	v_pk_fma_f32 v[248:249], v[244:245], v[250:251], v[248:249]
	v_cvt_pk_bf16_f32 v131, v252, v253
	v_lshlrev_b32_e32 v252, 16, v133
	v_and_b32_e32 v253, 0xffff0000, v133
	v_lshlrev_b32_e32 v254, 16, v227
	v_and_b32_e32 v255, 0xffff0000, v227
	v_pk_fma_f32 v[252:253], v[246:247], v[254:255], v[252:253]
	v_cvt_pk_bf16_f32 v132, v248, v249
	s_nop 0
	v_cvt_pk_bf16_f32 v133, v252, v253
	s_waitcnt vmcnt(4)
	v_lshlrev_b32_e32 v248, 16, v134
	v_and_b32_e32 v249, 0xffff0000, v134
	v_lshlrev_b32_e32 v250, 16, v228
	v_and_b32_e32 v251, 0xffff0000, v228
	v_pk_fma_f32 v[248:249], v[240:241], v[250:251], v[248:249]
	v_lshlrev_b32_e32 v252, 16, v135
	v_and_b32_e32 v253, 0xffff0000, v135
	v_lshlrev_b32_e32 v254, 16, v229
	v_and_b32_e32 v255, 0xffff0000, v229
	v_pk_fma_f32 v[252:253], v[242:243], v[254:255], v[252:253]
	v_cvt_pk_bf16_f32 v134, v248, v249
	v_lshlrev_b32_e32 v248, 16, v136
	v_and_b32_e32 v249, 0xffff0000, v136
	v_lshlrev_b32_e32 v250, 16, v230
	v_and_b32_e32 v251, 0xffff0000, v230
	v_pk_fma_f32 v[248:249], v[244:245], v[250:251], v[248:249]
	v_cvt_pk_bf16_f32 v135, v252, v253
	v_lshlrev_b32_e32 v252, 16, v137
	v_and_b32_e32 v253, 0xffff0000, v137
	v_lshlrev_b32_e32 v254, 16, v231
	v_and_b32_e32 v255, 0xffff0000, v231
	v_pk_fma_f32 v[252:253], v[246:247], v[254:255], v[252:253]
	v_cvt_pk_bf16_f32 v136, v248, v249
	s_nop 0
	v_cvt_pk_bf16_f32 v137, v252, v253
	s_waitcnt vmcnt(2)
	v_lshlrev_b32_e32 v248, 16, v138
	v_and_b32_e32 v249, 0xffff0000, v138
	v_lshlrev_b32_e32 v250, 16, v232
	v_and_b32_e32 v251, 0xffff0000, v232
	v_pk_fma_f32 v[248:249], v[240:241], v[250:251], v[248:249]
	v_lshlrev_b32_e32 v252, 16, v139
	v_and_b32_e32 v253, 0xffff0000, v139
	v_lshlrev_b32_e32 v254, 16, v233
	v_and_b32_e32 v255, 0xffff0000, v233
	v_pk_fma_f32 v[252:253], v[242:243], v[254:255], v[252:253]
	v_cvt_pk_bf16_f32 v138, v248, v249
	v_lshlrev_b32_e32 v248, 16, v140
	v_and_b32_e32 v249, 0xffff0000, v140
	v_lshlrev_b32_e32 v250, 16, v234
	v_and_b32_e32 v251, 0xffff0000, v234
	v_pk_fma_f32 v[248:249], v[244:245], v[250:251], v[248:249]
	v_cvt_pk_bf16_f32 v139, v252, v253
	v_lshlrev_b32_e32 v252, 16, v141
	v_and_b32_e32 v253, 0xffff0000, v141
	v_lshlrev_b32_e32 v254, 16, v235
	v_and_b32_e32 v255, 0xffff0000, v235
	v_pk_fma_f32 v[252:253], v[246:247], v[254:255], v[252:253]
	v_cvt_pk_bf16_f32 v140, v248, v249
	s_nop 0
	v_cvt_pk_bf16_f32 v141, v252, v253
	s_waitcnt vmcnt(0)
	v_lshlrev_b32_e32 v248, 16, v142
	v_and_b32_e32 v249, 0xffff0000, v142
	v_lshlrev_b32_e32 v250, 16, v236
	v_and_b32_e32 v251, 0xffff0000, v236
	v_pk_fma_f32 v[248:249], v[240:241], v[250:251], v[248:249]
	v_lshlrev_b32_e32 v252, 16, v143
	v_and_b32_e32 v253, 0xffff0000, v143
	v_lshlrev_b32_e32 v254, 16, v237
	v_and_b32_e32 v255, 0xffff0000, v237
	v_pk_fma_f32 v[252:253], v[242:243], v[254:255], v[252:253]
	v_cvt_pk_bf16_f32 v142, v248, v249
	v_lshlrev_b32_e32 v248, 16, v144
	v_and_b32_e32 v249, 0xffff0000, v144
	v_lshlrev_b32_e32 v250, 16, v238
	v_and_b32_e32 v251, 0xffff0000, v238
	v_pk_fma_f32 v[248:249], v[244:245], v[250:251], v[248:249]
	v_cvt_pk_bf16_f32 v143, v252, v253
	v_lshlrev_b32_e32 v252, 16, v145
	v_and_b32_e32 v253, 0xffff0000, v145
	v_lshlrev_b32_e32 v254, 16, v239
	v_and_b32_e32 v255, 0xffff0000, v239
	v_pk_fma_f32 v[252:253], v[246:247], v[254:255], v[252:253]
	v_cvt_pk_bf16_f32 v144, v248, v249
	s_nop 0
	v_cvt_pk_bf16_f32 v145, v252, v253
	s_lshl_b32 s6, s6, 8
	s_xor_b32 s6, s6, 0x100
	s_mulk_i32 s6, 0x90
	v_add_u32_e32 v146, s6, v193
	ds_write_b128 v146, v[130:133]
	ds_write_b128 v146, v[134:137] offset:9216
	ds_write_b128 v146, v[138:141] offset:18432
	ds_write_b128 v146, v[142:145] offset:27648
	ds_read_b128 v[130:133], v203 offset:64
	ds_read_b128 v[134:137], v203 offset:2368
	ds_read_b128 v[138:141], v190 offset:64
	ds_read_b128 v[142:145], v190 offset:2368
	ds_read_b128 v[146:149], v203 offset:4672
	ds_read_b128 v[150:153], v203 offset:6976
	v_lshl_add_u64 v[158:159], v[208:209], 0, s[16:17]
	s_waitcnt lgkmcnt(3)
	v_mfma_f32_16x16x32_bf16 v[126:129], v[130:133], v[138:141], v[126:129]
	v_add_u32_e32 v203, s6, v210
	v_mfma_f32_16x16x32_bf16 v[122:125], v[134:137], v[138:141], v[122:125]
	s_waitcnt lgkmcnt(1)
	v_mfma_f32_16x16x32_bf16 v[118:121], v[146:149], v[138:141], v[118:121]
	s_waitcnt lgkmcnt(0)
	v_mfma_f32_16x16x32_bf16 v[114:117], v[150:153], v[138:141], v[114:117]
	v_mfma_f32_16x16x32_bf16 v[110:113], v[130:133], v[142:145], v[110:113]
	v_mfma_f32_16x16x32_bf16 v[106:109], v[134:137], v[142:145], v[106:109]
	v_mfma_f32_16x16x32_bf16 v[102:105], v[146:149], v[142:145], v[102:105]
	v_mfma_f32_16x16x32_bf16 v[98:101], v[150:153], v[142:145], v[98:101]
	ds_read_b128 v[138:141], v190 offset:4672
	ds_read_b128 v[142:145], v190 offset:6976
	s_waitcnt lgkmcnt(1)
	v_mfma_f32_16x16x32_bf16 v[94:97], v[130:133], v[138:141], v[94:97]
	v_mfma_f32_16x16x32_bf16 v[90:93], v[134:137], v[138:141], v[90:93]
	v_mfma_f32_16x16x32_bf16 v[78:81], v[146:149], v[138:141], v[78:81]
	v_mfma_f32_16x16x32_bf16 v[66:69], v[150:153], v[138:141], v[66:69]
	v_add_co_u32_e32 v138, vcc, s53, v158
	s_nop 1
	v_addc_co_u32_e32 v139, vcc, 0, v159, vcc
	v_add_co_u32_e32 v154, vcc, s56, v158
	s_waitcnt lgkmcnt(0)
	v_mfma_f32_16x16x32_bf16 v[70:73], v[130:133], v[142:145], v[70:73]
	v_addc_co_u32_e32 v155, vcc, 0, v159, vcc
	v_add_co_u32_e32 v160, vcc, s57, v158
	global_load_dwordx4 v[138:141], v[138:139], off offset:128
	s_nop 0
	global_load_dwordx4 v[154:157], v[154:155], off offset:128
	v_addc_co_u32_e32 v161, vcc, 0, v159, vcc
	v_add_co_u32_e32 v162, vcc, s58, v158
	v_mfma_f32_16x16x32_bf16 v[82:85], v[134:137], v[142:145], v[82:85]
	s_nop 0
	v_addc_co_u32_e32 v163, vcc, 0, v159, vcc
	global_load_dwordx4 v[158:161], v[160:161], off offset:128
	s_nop 0
	global_load_dwordx4 v[162:165], v[162:163], off offset:128
	v_mfma_f32_16x16x32_bf16 v[74:77], v[146:149], v[142:145], v[74:77]
	v_mfma_f32_16x16x32_bf16 v[86:89], v[150:153], v[142:145], v[86:89]
	s_setprio 1
	s_setprio 0
	ds_read_b128 v[142:145], v190 offset:9280
	ds_read_b128 v[166:169], v190 offset:11584
	ds_read_b128 v[170:173], v190 offset:13888
	ds_read_b128 v[174:177], v190 offset:16192
	s_setprio 1
	s_waitcnt lgkmcnt(3)
	v_mfma_f32_16x16x32_bf16 v[62:65], v[130:133], v[142:145], v[62:65]
	v_mfma_f32_16x16x32_bf16 v[58:61], v[134:137], v[142:145], v[58:61]
	v_mfma_f32_16x16x32_bf16 v[54:57], v[146:149], v[142:145], v[54:57]
	v_mfma_f32_16x16x32_bf16 v[50:53], v[150:153], v[142:145], v[50:53]
	s_waitcnt lgkmcnt(2)
	v_mfma_f32_16x16x32_bf16 v[46:49], v[130:133], v[166:169], v[46:49]
	v_mfma_f32_16x16x32_bf16 v[42:45], v[134:137], v[166:169], v[42:45]
	v_mfma_f32_16x16x32_bf16 v[38:41], v[146:149], v[166:169], v[38:41]
	v_mfma_f32_16x16x32_bf16 v[34:37], v[150:153], v[166:169], v[34:37]
	s_waitcnt lgkmcnt(1)
	v_mfma_f32_16x16x32_bf16 v[30:33], v[130:133], v[170:173], v[30:33]
	v_mfma_f32_16x16x32_bf16 v[26:29], v[134:137], v[170:173], v[26:29]
	v_mfma_f32_16x16x32_bf16 v[22:25], v[146:149], v[170:173], v[22:25]
	v_mfma_f32_16x16x32_bf16 v[18:21], v[150:153], v[170:173], v[18:21]
	s_waitcnt lgkmcnt(0)
	v_mfma_f32_16x16x32_bf16 v[14:17], v[130:133], v[174:177], v[14:17]
	v_mfma_f32_16x16x32_bf16 v[10:13], v[134:137], v[174:177], v[10:13]
	v_mfma_f32_16x16x32_bf16 v[6:9], v[146:149], v[174:177], v[6:9]
	v_mfma_f32_16x16x32_bf16 v[2:5], v[150:153], v[174:177], v[2:5]
	s_setprio 0
	s_add_u32 s16, s16, 0x80
	s_addc_u32 s17, s17, 0
	s_cmpk_lg_i32 s16, 0x780
	v_lshl_add_u64 v[206:207], v[206:207], 0, s[10:11]
	s_waitcnt vmcnt(3)
	ds_write_b128 v203, v[138:141]
	s_waitcnt vmcnt(2)
	ds_write_b128 v203, v[154:157] offset:9216
	s_waitcnt vmcnt(1)
	ds_write_b128 v203, v[158:161] offset:18432
	s_waitcnt vmcnt(0)
	ds_write_b128 v203, v[162:165] offset:27648
	s_waitcnt lgkmcnt(0)
	s_barrier
	s_cbranch_scc1 .LBB0_513
	ds_read_b128 v[130:133], v189 offset:43776
	ds_read_b128 v[134:137], v189 offset:41472
	ds_read_b128 v[138:141], v189 offset:39168
	ds_read_b128 v[142:145], v189 offset:36864
	ds_read_b128 v[146:149], v218 offset:43776
	ds_read_b128 v[150:153], v218 offset:41472
	ds_read_b128 v[154:157], v218 offset:39168
	ds_read_b128 v[158:161], v218 offset:36864
	s_setprio 1
	s_waitcnt lgkmcnt(0)
	v_mfma_f32_16x16x32_bf16 v[126:129], v[158:161], v[142:145], v[126:129]
	v_mfma_f32_16x16x32_bf16 v[122:125], v[154:157], v[142:145], v[122:125]
	v_mfma_f32_16x16x32_bf16 v[118:121], v[150:153], v[142:145], v[118:121]
	v_mfma_f32_16x16x32_bf16 v[114:117], v[146:149], v[142:145], v[114:117]
	v_mfma_f32_16x16x32_bf16 v[110:113], v[158:161], v[138:141], v[110:113]
	v_mfma_f32_16x16x32_bf16 v[106:109], v[154:157], v[138:141], v[106:109]
	v_mfma_f32_16x16x32_bf16 v[102:105], v[150:153], v[138:141], v[102:105]
	v_mfma_f32_16x16x32_bf16 v[98:101], v[146:149], v[138:141], v[98:101]
	v_mfma_f32_16x16x32_bf16 v[94:97], v[158:161], v[134:137], v[94:97]
	v_mfma_f32_16x16x32_bf16 v[90:93], v[154:157], v[134:137], v[90:93]
	v_mfma_f32_16x16x32_bf16 v[78:81], v[150:153], v[134:137], v[78:81]
	v_mfma_f32_16x16x32_bf16 v[66:69], v[146:149], v[134:137], v[66:69]
	v_mfma_f32_16x16x32_bf16 v[70:73], v[158:161], v[130:133], v[70:73]
	v_mfma_f32_16x16x32_bf16 v[134:137], v[154:157], v[130:133], v[82:85]
	v_mfma_f32_16x16x32_bf16 v[138:141], v[150:153], v[130:133], v[74:77]
	v_mfma_f32_16x16x32_bf16 v[130:133], v[146:149], v[130:133], v[86:89]
	s_setprio 0
	s_nop 0
	ds_read_b128 v[74:77], v189 offset:46080
	ds_read_b128 v[82:85], v189 offset:48384
	ds_read_b128 v[86:89], v189 offset:50688
	ds_read_b128 v[142:145], v189 offset:52992
	s_setprio 1
	s_waitcnt lgkmcnt(3)
	v_mfma_f32_16x16x32_bf16 v[62:65], v[158:161], v[74:77], v[62:65]
	v_mfma_f32_16x16x32_bf16 v[58:61], v[154:157], v[74:77], v[58:61]
	v_mfma_f32_16x16x32_bf16 v[54:57], v[150:153], v[74:77], v[54:57]
	v_mfma_f32_16x16x32_bf16 v[50:53], v[146:149], v[74:77], v[50:53]
	s_waitcnt lgkmcnt(2)
	v_mfma_f32_16x16x32_bf16 v[46:49], v[158:161], v[82:85], v[46:49]
	v_mfma_f32_16x16x32_bf16 v[42:45], v[154:157], v[82:85], v[42:45]
	v_mfma_f32_16x16x32_bf16 v[38:41], v[150:153], v[82:85], v[38:41]
	v_mfma_f32_16x16x32_bf16 v[34:37], v[146:149], v[82:85], v[34:37]
	s_waitcnt lgkmcnt(1)
	v_mfma_f32_16x16x32_bf16 v[30:33], v[158:161], v[86:89], v[30:33]
	v_mfma_f32_16x16x32_bf16 v[26:29], v[154:157], v[86:89], v[26:29]
	v_mfma_f32_16x16x32_bf16 v[22:25], v[150:153], v[86:89], v[22:25]
	v_mfma_f32_16x16x32_bf16 v[18:21], v[146:149], v[86:89], v[18:21]
	s_waitcnt lgkmcnt(0)
	v_mfma_f32_16x16x32_bf16 v[14:17], v[158:161], v[142:145], v[14:17]
	v_mfma_f32_16x16x32_bf16 v[10:13], v[154:157], v[142:145], v[10:13]
	v_mfma_f32_16x16x32_bf16 v[6:9], v[150:153], v[142:145], v[6:9]
	v_mfma_f32_16x16x32_bf16 v[2:5], v[146:149], v[142:145], v[2:5]
	s_setprio 0
	ds_read_b128 v[142:145], v189 offset:43840
	ds_read_b128 v[74:77], v189 offset:41536
	ds_read_b128 v[82:85], v189 offset:39232
	ds_read_b128 v[86:89], v189 offset:36928
	ds_read_b128 v[146:149], v218 offset:36928
	ds_read_b128 v[150:153], v218 offset:39232
	ds_read_b128 v[154:157], v218 offset:41536
	ds_read_b128 v[158:161], v218 offset:43840
	s_setprio 1
	s_waitcnt lgkmcnt(3)
	v_mfma_f32_16x16x32_bf16 v[126:129], v[146:149], v[86:89], v[126:129]
	s_waitcnt lgkmcnt(2)
	v_mfma_f32_16x16x32_bf16 v[122:125], v[150:153], v[86:89], v[122:125]
	s_waitcnt lgkmcnt(1)
	v_mfma_f32_16x16x32_bf16 v[118:121], v[154:157], v[86:89], v[118:121]
	s_waitcnt lgkmcnt(0)
	v_mfma_f32_16x16x32_bf16 v[114:117], v[158:161], v[86:89], v[114:117]
	v_mfma_f32_16x16x32_bf16 v[110:113], v[146:149], v[82:85], v[110:113]
	v_mfma_f32_16x16x32_bf16 v[106:109], v[150:153], v[82:85], v[106:109]
	v_mfma_f32_16x16x32_bf16 v[102:105], v[154:157], v[82:85], v[102:105]
	v_mfma_f32_16x16x32_bf16 v[98:101], v[158:161], v[82:85], v[98:101]
	v_mfma_f32_16x16x32_bf16 v[94:97], v[146:149], v[74:77], v[94:97]
	v_mfma_f32_16x16x32_bf16 v[90:93], v[150:153], v[74:77], v[90:93]
	v_mfma_f32_16x16x32_bf16 v[86:89], v[154:157], v[74:77], v[78:81]
	v_mfma_f32_16x16x32_bf16 v[82:85], v[158:161], v[74:77], v[66:69]
	v_mfma_f32_16x16x32_bf16 v[78:81], v[146:149], v[142:145], v[70:73]
	v_mfma_f32_16x16x32_bf16 v[74:77], v[150:153], v[142:145], v[134:137]
	v_mfma_f32_16x16x32_bf16 v[70:73], v[154:157], v[142:145], v[138:141]
	v_mfma_f32_16x16x32_bf16 v[66:69], v[158:161], v[142:145], v[130:133]
	s_setprio 0
	s_nop 1
	ds_read_b128 v[130:133], v189 offset:46144
	ds_read_b128 v[134:137], v189 offset:48448
	ds_read_b128 v[138:141], v189 offset:50752
	ds_read_b128 v[142:145], v189 offset:53056
	s_setprio 1
	s_waitcnt lgkmcnt(3)
	v_mfma_f32_16x16x32_bf16 v[62:65], v[146:149], v[130:133], v[62:65]
	v_mfma_f32_16x16x32_bf16 v[58:61], v[150:153], v[130:133], v[58:61]
	v_mfma_f32_16x16x32_bf16 v[54:57], v[154:157], v[130:133], v[54:57]
	v_mfma_f32_16x16x32_bf16 v[50:53], v[158:161], v[130:133], v[50:53]
	s_waitcnt lgkmcnt(2)
	v_mfma_f32_16x16x32_bf16 v[46:49], v[146:149], v[134:137], v[46:49]
	v_mfma_f32_16x16x32_bf16 v[42:45], v[150:153], v[134:137], v[42:45]
	v_mfma_f32_16x16x32_bf16 v[38:41], v[154:157], v[134:137], v[38:41]
	v_mfma_f32_16x16x32_bf16 v[34:37], v[158:161], v[134:137], v[34:37]
	s_waitcnt lgkmcnt(1)
	v_mfma_f32_16x16x32_bf16 v[30:33], v[146:149], v[138:141], v[30:33]
	v_mfma_f32_16x16x32_bf16 v[26:29], v[150:153], v[138:141], v[26:29]
	v_mfma_f32_16x16x32_bf16 v[22:25], v[154:157], v[138:141], v[22:25]
	v_mfma_f32_16x16x32_bf16 v[18:21], v[158:161], v[138:141], v[18:21]
	s_waitcnt lgkmcnt(0)
	v_mfma_f32_16x16x32_bf16 v[14:17], v[146:149], v[142:145], v[14:17]
	v_mfma_f32_16x16x32_bf16 v[10:13], v[150:153], v[142:145], v[10:13]
	v_mfma_f32_16x16x32_bf16 v[6:9], v[154:157], v[142:145], v[6:9]
	v_mfma_f32_16x16x32_bf16 v[2:5], v[158:161], v[142:145], v[2:5]
	s_setprio 0
	v_lshl_or_b32 v156, s63, 8, v220
	v_lshlrev_b32_e32 v190, 1, v156
	v_lshrrev_b32_e32 v130, 4, v156
	v_mov_b32_e32 v131, v191
	v_add_u32_e32 v157, s64, v219
	v_lshl_add_u64 v[150:151], v[194:195], 0, v[190:191]
	v_lshl_add_u64 v[148:149], v[196:197], 0, v[190:191]
	v_lshl_add_u64 v[146:147], s[8:9], 0, v[130:131]
	s_mov_b64 s[16:17], -1
	s_and_b64 vcc, exec, s[14:15]
	s_barrier
	s_cbranch_vccz .LBB0_542
	s_and_b64 vcc, exec, s[12:13]
	s_cbranch_vccz .LBB0_517
	v_or_b32_e32 v130, v157, v215
	v_ashrrev_i32_e32 v131, 31, v130
	v_lshlrev_b64 v[132:133], 11, v[130:131]
	v_lshl_add_u64 v[132:133], v[150:151], 0, v[132:133]
	v_cvt_pk_bf16_f32 v134, v126, v127
	v_cvt_pk_bf16_f32 v135, v128, v129
	global_store_dwordx2 v[132:133], v[134:135], off
	v_cvt_pk_bf16_f32 v134, v122, v123
	v_cvt_pk_bf16_f32 v135, v124, v125
	global_store_dwordx2 v[132:133], v[134:135], off offset:32
	v_cvt_pk_bf16_f32 v134, v118, v119
	v_cvt_pk_bf16_f32 v135, v120, v121
	global_store_dwordx2 v[132:133], v[134:135], off offset:64
	v_cvt_pk_bf16_f32 v134, v114, v115
	v_cvt_pk_bf16_f32 v135, v116, v117
	global_store_dwordx2 v[132:133], v[134:135], off offset:96
	v_or_b32_e32 v132, 16, v130
	v_ashrrev_i32_e32 v133, 31, v132
	v_lshlrev_b64 v[132:133], 11, v[132:133]
	v_lshl_add_u64 v[132:133], v[150:151], 0, v[132:133]
	v_cvt_pk_bf16_f32 v134, v110, v111
	v_cvt_pk_bf16_f32 v135, v112, v113
	global_store_dwordx2 v[132:133], v[134:135], off
	v_cvt_pk_bf16_f32 v134, v106, v107
	v_cvt_pk_bf16_f32 v135, v108, v109
	global_store_dwordx2 v[132:133], v[134:135], off offset:32
	v_cvt_pk_bf16_f32 v134, v102, v103
	v_cvt_pk_bf16_f32 v135, v104, v105
	global_store_dwordx2 v[132:133], v[134:135], off offset:64
	v_cvt_pk_bf16_f32 v134, v98, v99
	v_cvt_pk_bf16_f32 v135, v100, v101
	global_store_dwordx2 v[132:133], v[134:135], off offset:96
	v_or_b32_e32 v132, 32, v130
	v_ashrrev_i32_e32 v133, 31, v132
	v_lshlrev_b64 v[132:133], 11, v[132:133]
	v_lshl_add_u64 v[132:133], v[150:151], 0, v[132:133]
	v_cvt_pk_bf16_f32 v134, v94, v95
	v_cvt_pk_bf16_f32 v135, v96, v97
	global_store_dwordx2 v[132:133], v[134:135], off
	v_cvt_pk_bf16_f32 v134, v90, v91
	v_cvt_pk_bf16_f32 v135, v92, v93
	v_or_b32_e32 v130, 48, v130
	global_store_dwordx2 v[132:133], v[134:135], off offset:32
	v_cvt_pk_bf16_f32 v134, v86, v87
	v_cvt_pk_bf16_f32 v135, v88, v89
	v_ashrrev_i32_e32 v131, 31, v130
	global_store_dwordx2 v[132:133], v[134:135], off offset:64
	v_cvt_pk_bf16_f32 v134, v82, v83
	v_cvt_pk_bf16_f32 v135, v84, v85
	v_lshlrev_b64 v[130:131], 11, v[130:131]
	global_store_dwordx2 v[132:133], v[134:135], off offset:96
	v_lshl_add_u64 v[130:131], v[150:151], 0, v[130:131]
	v_cvt_pk_bf16_f32 v132, v78, v79
	v_cvt_pk_bf16_f32 v133, v80, v81
	global_store_dwordx2 v[130:131], v[132:133], off
	v_cvt_pk_bf16_f32 v132, v74, v75
	v_cvt_pk_bf16_f32 v133, v76, v77
	global_store_dwordx2 v[130:131], v[132:133], off offset:32
	v_cvt_pk_bf16_f32 v132, v70, v71
	v_cvt_pk_bf16_f32 v133, v72, v73
	global_store_dwordx2 v[130:131], v[132:133], off offset:64
	v_cvt_pk_bf16_f32 v132, v66, v67
	v_cvt_pk_bf16_f32 v133, v68, v69
	global_store_dwordx2 v[130:131], v[132:133], off offset:96
	s_mov_b64 s[16:17], 0
